# code placement: the ten GEMM main-loop heads and two attention loop heads aligned to 64 bytes (.p2align 6)
# speedup vs baseline: 1.0058x; 1.0031x over previous
.LBB0_69:
	v_and_b32_e32 v19, 15, v18
	s_waitcnt vmcnt(0)
	v_and_b32_e32 v20, 48, v18
	v_lshlrev_b32_e32 v18, 2, v18
	v_lshlrev_b32_e32 v19, 6, v19
	v_and_b32_e32 v18, 32, v18
	s_lshl_b32 s18, s18, 12
	v_lshl_add_u64 v[8:9], v[8:9], 0, s[24:25]
	s_add_i32 m0, s17, 0x18000
	v_or_b32_e32 v21, v19, v20
	s_lshl_b32 s19, s19, 13
	v_bitop3_b32 v19, v19, v18, v20 bitop3:0x36
	s_and_b32 s18, s18, 0x3000
	s_waitcnt vmcnt(2)
	s_barrier
	global_load_lds_dwordx4 v[8:9], off
	v_lshl_add_u64 v[6:7], v[6:7], 0, s[24:25]
	s_add_i32 m0, s17, 0x1a000
	s_add_i32 s46, s17, 0x8000
	s_add_i32 s47, s17, 0xa000
	v_or_b32_e32 v141, s18, v19
	global_load_lds_dwordx4 v[6:7], off
	v_lshl_add_u64 v[4:5], v[4:5], 0, s[24:25]
	s_mov_b32 m0, s46
	s_add_u32 s18, s2, 0xb0080
	v_bitop3_b32 v18, v21, s19, v18 bitop3:0xde
	global_load_lds_dwordx4 v[4:5], off
	v_lshl_add_u64 v[2:3], v[2:3], 0, s[24:25]
	s_mov_b32 m0, s47
	s_addc_u32 s19, s3, 0
	global_load_lds_dwordx4 v[2:3], off
	v_lshl_add_u64 v[2:3], s[18:19], 0, v[0:1]
	s_add_i32 m0, s17, 0x1c000
	s_movk_i32 s40, 0xb00
	global_load_lds_dwordx4 v[2:3], off
	v_lshl_add_u64 v[2:3], s[18:19], 0, v[134:135]
	s_add_i32 m0, s17, 0x1e000
	s_mov_b32 s20, 0xb000
	global_load_lds_dwordx4 v[2:3], off
	v_lshrrev_b32_e32 v3, 1, v14
	v_mul_lo_u32 v2, v16, s40
	v_mad_u64_u32 v[2:3], s[18:19], v3, s20, v[2:3]
	v_or_b32_e32 v2, v2, v15
	s_add_u32 s8, s72, s8
	v_add_lshl_u32 v2, v2, v17, 1
	v_mov_b32_e32 v3, v1
	s_addc_u32 s9, s73, s9
	v_lshl_add_u64 v[136:137], s[8:9], 0, v[2:3]
	v_lshrrev_b32_e32 v3, 1, v10
	v_mul_lo_u32 v2, v12, s40
	v_mad_u64_u32 v[2:3], s[18:19], v3, s20, v[2:3]
	v_or_b32_e32 v2, v2, v11
	s_waitcnt vmcnt(6)
	v_add_lshl_u32 v2, v2, v13, 1
	v_mov_b32_e32 v3, v1
	v_lshl_add_u64 v[138:139], s[8:9], 0, v[2:3]
	v_mov_b32_e32 v2, 0
	s_mov_b32 s58, -2
	s_mov_b64 s[8:9], 0x61f8080
	v_add_u32_e32 v142, 0, v18
	v_mov_b32_e32 v3, v2
	v_mov_b32_e32 v4, v2
	v_mov_b32_e32 v5, v2
	v_mov_b32_e32 v6, v2
	v_mov_b32_e32 v7, v2
	v_mov_b32_e32 v8, v2
	v_mov_b32_e32 v9, v2
	v_mov_b32_e32 v10, v2
	v_mov_b32_e32 v11, v2
	v_mov_b32_e32 v12, v2
	v_mov_b32_e32 v13, v2
	v_mov_b32_e32 v14, v2
	v_mov_b32_e32 v15, v2
	v_mov_b32_e32 v16, v2
	v_mov_b32_e32 v17, v2
	v_mov_b32_e32 v26, v2
	v_mov_b32_e32 v27, v2
	v_mov_b32_e32 v28, v2
	v_mov_b32_e32 v29, v2
	v_mov_b32_e32 v30, v2
	v_mov_b32_e32 v31, v2
	v_mov_b32_e32 v32, v2
	v_mov_b32_e32 v33, v2
	v_mov_b32_e32 v42, v2
	v_mov_b32_e32 v43, v2
	v_mov_b32_e32 v44, v2
	v_mov_b32_e32 v45, v2
	v_mov_b32_e32 v46, v2
	v_mov_b32_e32 v47, v2
	v_mov_b32_e32 v48, v2
	v_mov_b32_e32 v49, v2
	v_mov_b32_e32 v18, v2
	v_mov_b32_e32 v19, v2
	v_mov_b32_e32 v20, v2
	v_mov_b32_e32 v21, v2
	v_mov_b32_e32 v22, v2
	v_mov_b32_e32 v23, v2
	v_mov_b32_e32 v24, v2
	v_mov_b32_e32 v25, v2
	v_mov_b32_e32 v34, v2
	v_mov_b32_e32 v35, v2
	v_mov_b32_e32 v36, v2
	v_mov_b32_e32 v37, v2
	v_mov_b32_e32 v38, v2
	v_mov_b32_e32 v39, v2
	v_mov_b32_e32 v40, v2
	v_mov_b32_e32 v41, v2
	v_mov_b32_e32 v50, v2
	v_mov_b32_e32 v51, v2
	v_mov_b32_e32 v52, v2
	v_mov_b32_e32 v53, v2
	v_mov_b32_e32 v54, v2
	v_mov_b32_e32 v55, v2
	v_mov_b32_e32 v56, v2
	v_mov_b32_e32 v57, v2
	v_mov_b32_e32 v58, v2
	v_mov_b32_e32 v59, v2
	v_mov_b32_e32 v60, v2
	v_mov_b32_e32 v61, v2
	v_mov_b32_e32 v62, v2
	v_mov_b32_e32 v63, v2
	v_mov_b32_e32 v64, v2
	v_mov_b32_e32 v65, v2
	v_mov_b32_e32 v66, v2
	v_mov_b32_e32 v67, v2
	v_mov_b32_e32 v68, v2
	v_mov_b32_e32 v69, v2
	v_mov_b32_e32 v70, v2
	v_mov_b32_e32 v71, v2
	v_mov_b32_e32 v72, v2
	v_mov_b32_e32 v73, v2
	v_mov_b32_e32 v74, v2
	v_mov_b32_e32 v75, v2
	v_mov_b32_e32 v76, v2
	v_mov_b32_e32 v77, v2
	v_mov_b32_e32 v78, v2
	v_mov_b32_e32 v79, v2
	v_mov_b32_e32 v80, v2
	v_mov_b32_e32 v81, v2
	v_mov_b32_e32 v90, v2
	v_mov_b32_e32 v91, v2
	v_mov_b32_e32 v92, v2
	v_mov_b32_e32 v93, v2
	v_mov_b32_e32 v94, v2
	v_mov_b32_e32 v95, v2
	v_mov_b32_e32 v96, v2
	v_mov_b32_e32 v97, v2
	v_mov_b32_e32 v106, v2
	v_mov_b32_e32 v107, v2
	v_mov_b32_e32 v108, v2
	v_mov_b32_e32 v109, v2
	v_mov_b32_e32 v110, v2
	v_mov_b32_e32 v111, v2
	v_mov_b32_e32 v112, v2
	v_mov_b32_e32 v113, v2
	v_mov_b32_e32 v82, v2
	v_mov_b32_e32 v83, v2
	v_mov_b32_e32 v84, v2
	v_mov_b32_e32 v85, v2
	v_mov_b32_e32 v86, v2
	v_mov_b32_e32 v87, v2
	v_mov_b32_e32 v88, v2
	v_mov_b32_e32 v89, v2
	v_mov_b32_e32 v98, v2
	v_mov_b32_e32 v99, v2
	v_mov_b32_e32 v100, v2
	v_mov_b32_e32 v101, v2
	v_mov_b32_e32 v102, v2
	v_mov_b32_e32 v103, v2
	v_mov_b32_e32 v104, v2
	v_mov_b32_e32 v105, v2
	v_mov_b32_e32 v114, v2
	v_mov_b32_e32 v115, v2
	v_mov_b32_e32 v116, v2
	v_mov_b32_e32 v117, v2
	v_mov_b32_e32 v118, v2
	v_mov_b32_e32 v119, v2
	v_mov_b32_e32 v120, v2
	v_mov_b32_e32 v121, v2
	v_mov_b32_e32 v122, v2
	v_mov_b32_e32 v123, v2
	v_mov_b32_e32 v124, v2
	v_mov_b32_e32 v125, v2
	v_mov_b32_e32 v126, v2
	v_mov_b32_e32 v127, v2
	v_mov_b32_e32 v128, v2
	v_mov_b32_e32 v129, v2
	s_barrier
	.p2align	6

.LBB0_80:
	v_and_b32_e32 v19, 15, v18
	s_waitcnt vmcnt(0)
	v_and_b32_e32 v20, 48, v18
	v_lshlrev_b32_e32 v18, 2, v18
	s_and_b32 s82, s10, 7
	v_lshlrev_b32_e32 v19, 6, v19
	v_and_b32_e32 v18, 32, v18
	s_lshl_b32 s58, s58, 12
	v_lshl_add_u64 v[8:9], v[8:9], 0, s[24:25]
	s_add_i32 m0, s16, 0x18000
	s_lshl_b32 s82, s82, 8
	v_or_b32_e32 v21, v19, v20
	s_lshl_b32 s59, s59, 13
	v_bitop3_b32 v19, v19, v18, v20 bitop3:0x36
	s_and_b32 s58, s58, 0x3000
	s_waitcnt vmcnt(2)
	s_barrier
	global_load_lds_dwordx4 v[8:9], off
	v_lshl_add_u64 v[6:7], v[6:7], 0, s[24:25]
	s_add_i32 m0, s16, 0x1a000
	s_add_i32 s86, s16, 0x8000
	s_add_i32 s87, s16, 0xa000
	v_or_b32_e32 v141, s58, v19
	global_load_lds_dwordx4 v[6:7], off
	v_lshl_add_u64 v[4:5], v[4:5], 0, s[24:25]
	s_mov_b32 m0, s86
	s_add_u32 s58, s42, 0x580080
	v_bitop3_b32 v18, v21, s59, v18 bitop3:0xde
	global_load_lds_dwordx4 v[4:5], off
	v_lshl_add_u64 v[2:3], v[2:3], 0, s[24:25]
	s_mov_b32 m0, s87
	s_addc_u32 s59, s43, 0
	global_load_lds_dwordx4 v[2:3], off
	v_lshl_add_u64 v[2:3], s[58:59], 0, v[0:1]
	s_add_i32 m0, s16, 0x1c000
	s_lshl_b32 s20, s20, 11
	global_load_lds_dwordx4 v[2:3], off
	v_lshl_add_u64 v[2:3], s[58:59], 0, v[134:135]
	s_add_i32 m0, s16, 0x1e000
	s_or_b32 s58, s20, s82
	global_load_lds_dwordx4 v[2:3], off
	v_lshlrev_b32_e32 v2, 13, v14
	s_ashr_i32 s59, s58, 31
	v_and_b32_e32 v2, 0x7fffc000, v2
	s_lshl_b64 s[58:59], s[58:59], 11
	v_lshl_add_u32 v2, v15, 10, v2
	v_or_b32_e32 v2, v2, v16
	s_add_u32 s58, s72, s58
	v_add_lshl_u32 v2, v2, v17, 1
	v_mov_b32_e32 v3, v1
	s_addc_u32 s59, s73, s59
	v_lshl_add_u64 v[136:137], s[58:59], 0, v[2:3]
	v_lshlrev_b32_e32 v2, 13, v10
	v_and_b32_e32 v2, 0x7fffc000, v2
	v_lshl_add_u32 v2, v11, 10, v2
	v_or_b32_e32 v2, v2, v12
	s_waitcnt vmcnt(6)
	v_add_lshl_u32 v2, v2, v13, 1
	v_lshl_add_u64 v[138:139], s[58:59], 0, v[2:3]
	v_mov_b32_e32 v2, 0
	s_mov_b32 s58, -2
	s_mov_b64 s[94:95], 0x3188080
	v_add_u32_e32 v142, 0, v18
	v_mov_b32_e32 v3, v2
	v_mov_b32_e32 v4, v2
	v_mov_b32_e32 v5, v2
	v_mov_b32_e32 v6, v2
	v_mov_b32_e32 v7, v2
	v_mov_b32_e32 v8, v2
	v_mov_b32_e32 v9, v2
	v_mov_b32_e32 v10, v2
	v_mov_b32_e32 v11, v2
	v_mov_b32_e32 v12, v2
	v_mov_b32_e32 v13, v2
	v_mov_b32_e32 v14, v2
	v_mov_b32_e32 v15, v2
	v_mov_b32_e32 v16, v2
	v_mov_b32_e32 v17, v2
	v_mov_b32_e32 v26, v2
	v_mov_b32_e32 v27, v2
	v_mov_b32_e32 v28, v2
	v_mov_b32_e32 v29, v2
	v_mov_b32_e32 v30, v2
	v_mov_b32_e32 v31, v2
	v_mov_b32_e32 v32, v2
	v_mov_b32_e32 v33, v2
	v_mov_b32_e32 v42, v2
	v_mov_b32_e32 v43, v2
	v_mov_b32_e32 v44, v2
	v_mov_b32_e32 v45, v2
	v_mov_b32_e32 v46, v2
	v_mov_b32_e32 v47, v2
	v_mov_b32_e32 v48, v2
	v_mov_b32_e32 v49, v2
	v_mov_b32_e32 v18, v2
	v_mov_b32_e32 v19, v2
	v_mov_b32_e32 v20, v2
	v_mov_b32_e32 v21, v2
	v_mov_b32_e32 v22, v2
	v_mov_b32_e32 v23, v2
	v_mov_b32_e32 v24, v2
	v_mov_b32_e32 v25, v2
	v_mov_b32_e32 v34, v2
	v_mov_b32_e32 v35, v2
	v_mov_b32_e32 v36, v2
	v_mov_b32_e32 v37, v2
	v_mov_b32_e32 v38, v2
	v_mov_b32_e32 v39, v2
	v_mov_b32_e32 v40, v2
	v_mov_b32_e32 v41, v2
	v_mov_b32_e32 v50, v2
	v_mov_b32_e32 v51, v2
	v_mov_b32_e32 v52, v2
	v_mov_b32_e32 v53, v2
	v_mov_b32_e32 v54, v2
	v_mov_b32_e32 v55, v2
	v_mov_b32_e32 v56, v2
	v_mov_b32_e32 v57, v2
	v_mov_b32_e32 v58, v2
	v_mov_b32_e32 v59, v2
	v_mov_b32_e32 v60, v2
	v_mov_b32_e32 v61, v2
	v_mov_b32_e32 v62, v2
	v_mov_b32_e32 v63, v2
	v_mov_b32_e32 v64, v2
	v_mov_b32_e32 v65, v2
	v_mov_b32_e32 v66, v2
	v_mov_b32_e32 v67, v2
	v_mov_b32_e32 v68, v2
	v_mov_b32_e32 v69, v2
	v_mov_b32_e32 v70, v2
	v_mov_b32_e32 v71, v2
	v_mov_b32_e32 v72, v2
	v_mov_b32_e32 v73, v2
	v_mov_b32_e32 v74, v2
	v_mov_b32_e32 v75, v2
	v_mov_b32_e32 v76, v2
	v_mov_b32_e32 v77, v2
	v_mov_b32_e32 v78, v2
	v_mov_b32_e32 v79, v2
	v_mov_b32_e32 v80, v2
	v_mov_b32_e32 v81, v2
	v_mov_b32_e32 v90, v2
	v_mov_b32_e32 v91, v2
	v_mov_b32_e32 v92, v2
	v_mov_b32_e32 v93, v2
	v_mov_b32_e32 v94, v2
	v_mov_b32_e32 v95, v2
	v_mov_b32_e32 v96, v2
	v_mov_b32_e32 v97, v2
	v_mov_b32_e32 v106, v2
	v_mov_b32_e32 v107, v2
	v_mov_b32_e32 v108, v2
	v_mov_b32_e32 v109, v2
	v_mov_b32_e32 v110, v2
	v_mov_b32_e32 v111, v2
	v_mov_b32_e32 v112, v2
	v_mov_b32_e32 v113, v2
	v_mov_b32_e32 v82, v2
	v_mov_b32_e32 v83, v2
	v_mov_b32_e32 v84, v2
	v_mov_b32_e32 v85, v2
	v_mov_b32_e32 v86, v2
	v_mov_b32_e32 v87, v2
	v_mov_b32_e32 v88, v2
	v_mov_b32_e32 v89, v2
	v_mov_b32_e32 v98, v2
	v_mov_b32_e32 v99, v2
	v_mov_b32_e32 v100, v2
	v_mov_b32_e32 v101, v2
	v_mov_b32_e32 v102, v2
	v_mov_b32_e32 v103, v2
	v_mov_b32_e32 v104, v2
	v_mov_b32_e32 v105, v2
	v_mov_b32_e32 v114, v2
	v_mov_b32_e32 v115, v2
	v_mov_b32_e32 v116, v2
	v_mov_b32_e32 v117, v2
	v_mov_b32_e32 v118, v2
	v_mov_b32_e32 v119, v2
	v_mov_b32_e32 v120, v2
	v_mov_b32_e32 v121, v2
	v_mov_b32_e32 v122, v2
	v_mov_b32_e32 v123, v2
	v_mov_b32_e32 v124, v2
	v_mov_b32_e32 v125, v2
	v_mov_b32_e32 v126, v2
	v_mov_b32_e32 v127, v2
	v_mov_b32_e32 v128, v2
	v_mov_b32_e32 v129, v2
	s_barrier
	.p2align	6

.LBB0_172:
	s_and_b32 s40, s5, 0xffffff00
	v_and_b32_e32 v19, 15, v18
	s_waitcnt vmcnt(0)
	v_and_b32_e32 v20, 48, v18
	v_lshlrev_b32_e32 v18, 2, v18
	s_ashr_i32 s41, s40, 31
	v_lshlrev_b32_e32 v19, 6, v19
	v_and_b32_e32 v18, 32, v18
	s_lshl_b32 s18, s18, 12
	v_lshl_add_u64 v[8:9], v[8:9], 0, s[24:25]
	s_add_i32 m0, s12, 0x18000
	s_lshl_b64 s[40:41], s[40:41], 11
	v_or_b32_e32 v21, v19, v20
	s_lshl_b32 s19, s19, 13
	v_bitop3_b32 v19, v19, v18, v20 bitop3:0x36
	s_and_b32 s18, s18, 0x3000
	s_waitcnt vmcnt(2)
	s_barrier
	global_load_lds_dwordx4 v[8:9], off
	v_lshl_add_u64 v[6:7], v[6:7], 0, s[24:25]
	s_add_i32 m0, s12, 0x1a000
	s_add_i32 s28, s12, 0x8000
	s_add_i32 s46, s12, 0xa000
	v_or_b32_e32 v141, s18, v19
	global_load_lds_dwordx4 v[6:7], off
	v_lshl_add_u64 v[4:5], v[4:5], 0, s[24:25]
	s_mov_b32 m0, s28
	s_add_u32 s18, s8, 0x40080
	v_bitop3_b32 v18, v21, s19, v18 bitop3:0xde
	global_load_lds_dwordx4 v[4:5], off
	v_lshl_add_u64 v[2:3], v[2:3], 0, s[24:25]
	s_mov_b32 m0, s46
	s_addc_u32 s19, s9, 0
	global_load_lds_dwordx4 v[2:3], off
	v_lshl_add_u64 v[2:3], s[18:19], 0, v[0:1]
	s_add_i32 m0, s12, 0x1c000
	s_mov_b32 s47, -2
	global_load_lds_dwordx4 v[2:3], off
	v_lshl_add_u64 v[2:3], s[18:19], 0, v[134:135]
	s_add_i32 m0, s12, 0x1e000
	s_add_u32 s18, s72, s40
	global_load_lds_dwordx4 v[2:3], off
	v_lshlrev_b32_e32 v2, 13, v14
	v_and_b32_e32 v2, 0x7fffc000, v2
	v_lshl_add_u32 v2, v15, 10, v2
	v_or_b32_e32 v2, v2, v16
	v_add_lshl_u32 v2, v2, v17, 1
	v_mov_b32_e32 v3, v1
	s_addc_u32 s19, s73, s41
	v_lshl_add_u64 v[136:137], s[18:19], 0, v[2:3]
	v_lshlrev_b32_e32 v2, 13, v10
	v_and_b32_e32 v2, 0x7fffc000, v2
	v_lshl_add_u32 v2, v11, 10, v2
	v_or_b32_e32 v2, v2, v12
	s_waitcnt vmcnt(6)
	v_add_lshl_u32 v2, v2, v13, 1
	v_lshl_add_u64 v[138:139], s[18:19], 0, v[2:3]
	v_mov_b32_e32 v2, 0
	s_mov_b64 s[18:19], 0xa988080
	v_add_u32_e32 v142, 0, v18
	v_mov_b32_e32 v3, v2
	v_mov_b32_e32 v4, v2
	v_mov_b32_e32 v5, v2
	v_mov_b32_e32 v6, v2
	v_mov_b32_e32 v7, v2
	v_mov_b32_e32 v8, v2
	v_mov_b32_e32 v9, v2
	v_mov_b32_e32 v10, v2
	v_mov_b32_e32 v11, v2
	v_mov_b32_e32 v12, v2
	v_mov_b32_e32 v13, v2
	v_mov_b32_e32 v14, v2
	v_mov_b32_e32 v15, v2
	v_mov_b32_e32 v16, v2
	v_mov_b32_e32 v17, v2
	v_mov_b32_e32 v26, v2
	v_mov_b32_e32 v27, v2
	v_mov_b32_e32 v28, v2
	v_mov_b32_e32 v29, v2
	v_mov_b32_e32 v30, v2
	v_mov_b32_e32 v31, v2
	v_mov_b32_e32 v32, v2
	v_mov_b32_e32 v33, v2
	v_mov_b32_e32 v42, v2
	v_mov_b32_e32 v43, v2
	v_mov_b32_e32 v44, v2
	v_mov_b32_e32 v45, v2
	v_mov_b32_e32 v46, v2
	v_mov_b32_e32 v47, v2
	v_mov_b32_e32 v48, v2
	v_mov_b32_e32 v49, v2
	v_mov_b32_e32 v18, v2
	v_mov_b32_e32 v19, v2
	v_mov_b32_e32 v20, v2
	v_mov_b32_e32 v21, v2
	v_mov_b32_e32 v22, v2
	v_mov_b32_e32 v23, v2
	v_mov_b32_e32 v24, v2
	v_mov_b32_e32 v25, v2
	v_mov_b32_e32 v34, v2
	v_mov_b32_e32 v35, v2
	v_mov_b32_e32 v36, v2
	v_mov_b32_e32 v37, v2
	v_mov_b32_e32 v38, v2
	v_mov_b32_e32 v39, v2
	v_mov_b32_e32 v40, v2
	v_mov_b32_e32 v41, v2
	v_mov_b32_e32 v50, v2
	v_mov_b32_e32 v51, v2
	v_mov_b32_e32 v52, v2
	v_mov_b32_e32 v53, v2
	v_mov_b32_e32 v54, v2
	v_mov_b32_e32 v55, v2
	v_mov_b32_e32 v56, v2
	v_mov_b32_e32 v57, v2
	v_mov_b32_e32 v58, v2
	v_mov_b32_e32 v59, v2
	v_mov_b32_e32 v60, v2
	v_mov_b32_e32 v61, v2
	v_mov_b32_e32 v62, v2
	v_mov_b32_e32 v63, v2
	v_mov_b32_e32 v64, v2
	v_mov_b32_e32 v65, v2
	v_mov_b32_e32 v66, v2
	v_mov_b32_e32 v67, v2
	v_mov_b32_e32 v68, v2
	v_mov_b32_e32 v69, v2
	v_mov_b32_e32 v70, v2
	v_mov_b32_e32 v71, v2
	v_mov_b32_e32 v72, v2
	v_mov_b32_e32 v73, v2
	v_mov_b32_e32 v74, v2
	v_mov_b32_e32 v75, v2
	v_mov_b32_e32 v76, v2
	v_mov_b32_e32 v77, v2
	v_mov_b32_e32 v78, v2
	v_mov_b32_e32 v79, v2
	v_mov_b32_e32 v80, v2
	v_mov_b32_e32 v81, v2
	v_mov_b32_e32 v90, v2
	v_mov_b32_e32 v91, v2
	v_mov_b32_e32 v92, v2
	v_mov_b32_e32 v93, v2
	v_mov_b32_e32 v94, v2
	v_mov_b32_e32 v95, v2
	v_mov_b32_e32 v96, v2
	v_mov_b32_e32 v97, v2
	v_mov_b32_e32 v106, v2
	v_mov_b32_e32 v107, v2
	v_mov_b32_e32 v108, v2
	v_mov_b32_e32 v109, v2
	v_mov_b32_e32 v110, v2
	v_mov_b32_e32 v111, v2
	v_mov_b32_e32 v112, v2
	v_mov_b32_e32 v113, v2
	v_mov_b32_e32 v82, v2
	v_mov_b32_e32 v83, v2
	v_mov_b32_e32 v84, v2
	v_mov_b32_e32 v85, v2
	v_mov_b32_e32 v86, v2
	v_mov_b32_e32 v87, v2
	v_mov_b32_e32 v88, v2
	v_mov_b32_e32 v89, v2
	v_mov_b32_e32 v98, v2
	v_mov_b32_e32 v99, v2
	v_mov_b32_e32 v100, v2
	v_mov_b32_e32 v101, v2
	v_mov_b32_e32 v102, v2
	v_mov_b32_e32 v103, v2
	v_mov_b32_e32 v104, v2
	v_mov_b32_e32 v105, v2
	v_mov_b32_e32 v114, v2
	v_mov_b32_e32 v115, v2
	v_mov_b32_e32 v116, v2
	v_mov_b32_e32 v117, v2
	v_mov_b32_e32 v118, v2
	v_mov_b32_e32 v119, v2
	v_mov_b32_e32 v120, v2
	v_mov_b32_e32 v121, v2
	v_mov_b32_e32 v122, v2
	v_mov_b32_e32 v123, v2
	v_mov_b32_e32 v124, v2
	v_mov_b32_e32 v125, v2
	v_mov_b32_e32 v126, v2
	v_mov_b32_e32 v127, v2
	v_mov_b32_e32 v128, v2
	v_mov_b32_e32 v129, v2
	s_barrier
	.p2align	6

.LBB0_335:
	s_add_u32 s20, s2, 0x200000
	s_addc_u32 s56, s3, 0
	s_cmp_eq_u32 s96, 2
	s_cselect_b64 s[2:3], -1, 0
	v_and_b32_e32 v0, 15, v8
	s_and_b64 s[10:11], s[2:3], exec
	v_and_b32_e32 v6, 48, v8
	v_lshlrev_b32_e32 v0, 6, v0
	v_lshlrev_b32_e32 v8, 2, v8
	s_cselect_b32 s97, s95, s56
	s_cselect_b32 vcc_lo, s94, s20
	v_or_b32_e32 v7, v0, v6
	s_lshl_b32 s7, s7, 13
	v_and_b32_e32 v8, 32, v8
	s_lshl_b32 s6, s6, 12
	v_bitop3_b32 v0, v0, v8, v6 bitop3:0x36
	v_bitop3_b32 v6, v7, s7, v8 bitop3:0xde
	s_and_b32 s6, s6, 0x3000
	v_lshl_add_u64 v[132:133], s[54:55], 0, v[2:3]
	v_mov_b32_e32 v2, 0
	v_or_b32_e32 v143, s6, v0
	v_lshl_add_u64 v[130:131], s[54:55], 0, v[4:5]
	s_mov_b32 vcc_hi, -2
	s_mov_b64 s[56:57], 0
	v_add_u32_e32 v144, 0, v6
	v_mov_b32_e32 v3, v2
	v_mov_b32_e32 v4, v2
	v_mov_b32_e32 v5, v2
	v_mov_b32_e32 v6, v2
	v_mov_b32_e32 v7, v2
	v_mov_b32_e32 v8, v2
	v_mov_b32_e32 v9, v2
	v_mov_b32_e32 v18, v2
	v_mov_b32_e32 v19, v2
	s_waitcnt vmcnt(0)
	v_mov_b32_e32 v20, v2
	v_mov_b32_e32 v21, v2
	v_mov_b32_e32 v22, v2
	v_mov_b32_e32 v23, v2
	v_mov_b32_e32 v24, v2
	v_mov_b32_e32 v25, v2
	v_mov_b32_e32 v34, v2
	v_mov_b32_e32 v35, v2
	v_mov_b32_e32 v36, v2
	v_mov_b32_e32 v37, v2
	v_mov_b32_e32 v38, v2
	v_mov_b32_e32 v39, v2
	v_mov_b32_e32 v40, v2
	v_mov_b32_e32 v41, v2
	v_mov_b32_e32 v50, v2
	v_mov_b32_e32 v51, v2
	v_mov_b32_e32 v52, v2
	v_mov_b32_e32 v53, v2
	v_mov_b32_e32 v54, v2
	v_mov_b32_e32 v55, v2
	v_mov_b32_e32 v56, v2
	v_mov_b32_e32 v57, v2
	v_mov_b32_e32 v10, v2
	v_mov_b32_e32 v11, v2
	v_mov_b32_e32 v12, v2
	v_mov_b32_e32 v13, v2
	v_mov_b32_e32 v14, v2
	v_mov_b32_e32 v15, v2
	v_mov_b32_e32 v16, v2
	v_mov_b32_e32 v17, v2
	v_mov_b32_e32 v26, v2
	v_mov_b32_e32 v27, v2
	v_mov_b32_e32 v28, v2
	v_mov_b32_e32 v29, v2
	v_mov_b32_e32 v30, v2
	v_mov_b32_e32 v31, v2
	v_mov_b32_e32 v32, v2
	v_mov_b32_e32 v33, v2
	v_mov_b32_e32 v42, v2
	v_mov_b32_e32 v43, v2
	v_mov_b32_e32 v44, v2
	v_mov_b32_e32 v45, v2
	v_mov_b32_e32 v46, v2
	v_mov_b32_e32 v47, v2
	v_mov_b32_e32 v48, v2
	v_mov_b32_e32 v49, v2
	v_mov_b32_e32 v58, v2
	v_mov_b32_e32 v59, v2
	v_mov_b32_e32 v60, v2
	v_mov_b32_e32 v61, v2
	v_mov_b32_e32 v62, v2
	v_mov_b32_e32 v63, v2
	v_mov_b32_e32 v64, v2
	v_mov_b32_e32 v65, v2
	v_mov_b32_e32 v66, v2
	v_mov_b32_e32 v67, v2
	v_mov_b32_e32 v68, v2
	v_mov_b32_e32 v69, v2
	v_mov_b32_e32 v70, v2
	v_mov_b32_e32 v71, v2
	v_mov_b32_e32 v72, v2
	v_mov_b32_e32 v73, v2
	v_mov_b32_e32 v82, v2
	v_mov_b32_e32 v83, v2
	v_mov_b32_e32 v84, v2
	v_mov_b32_e32 v85, v2
	v_mov_b32_e32 v86, v2
	v_mov_b32_e32 v87, v2
	v_mov_b32_e32 v88, v2
	v_mov_b32_e32 v89, v2
	v_mov_b32_e32 v98, v2
	v_mov_b32_e32 v99, v2
	v_mov_b32_e32 v100, v2
	v_mov_b32_e32 v101, v2
	v_mov_b32_e32 v102, v2
	v_mov_b32_e32 v103, v2
	v_mov_b32_e32 v104, v2
	v_mov_b32_e32 v105, v2
	v_mov_b32_e32 v114, v2
	v_mov_b32_e32 v115, v2
	v_mov_b32_e32 v116, v2
	v_mov_b32_e32 v117, v2
	v_mov_b32_e32 v118, v2
	v_mov_b32_e32 v119, v2
	v_mov_b32_e32 v120, v2
	v_mov_b32_e32 v121, v2
	v_mov_b32_e32 v74, v2
	v_mov_b32_e32 v75, v2
	v_mov_b32_e32 v76, v2
	v_mov_b32_e32 v77, v2
	v_mov_b32_e32 v78, v2
	v_mov_b32_e32 v79, v2
	v_mov_b32_e32 v80, v2
	v_mov_b32_e32 v81, v2
	v_mov_b32_e32 v90, v2
	v_mov_b32_e32 v91, v2
	v_mov_b32_e32 v92, v2
	v_mov_b32_e32 v93, v2
	v_mov_b32_e32 v94, v2
	v_mov_b32_e32 v95, v2
	v_mov_b32_e32 v96, v2
	v_mov_b32_e32 v97, v2
	v_mov_b32_e32 v106, v2
	v_mov_b32_e32 v107, v2
	v_mov_b32_e32 v108, v2
	v_mov_b32_e32 v109, v2
	v_mov_b32_e32 v110, v2
	v_mov_b32_e32 v111, v2
	v_mov_b32_e32 v112, v2
	v_mov_b32_e32 v113, v2
	v_mov_b32_e32 v122, v2
	v_mov_b32_e32 v123, v2
	v_mov_b32_e32 v124, v2
	v_mov_b32_e32 v125, v2
	v_mov_b32_e32 v126, v2
	v_mov_b32_e32 v127, v2
	v_mov_b32_e32 v128, v2
	v_mov_b32_e32 v129, v2
	.p2align	6

.LBB0_340:
	s_cmp_eq_u32 s56, 2
	s_mov_b32 s20, s56
	s_cselect_b64 s[8:9], -1, 0
	s_add_i32 s56, s56, 1
	s_cmp_lg_u32 s20, 2
	s_cselect_b64 s[2:3], -1, 0
	s_and_b64 s[18:19], s[2:3], exec
	s_cselect_b32 s18, s56, 2
	s_cmp_eq_u32 s20, 1
	s_mov_b32 s40, 0x7948000
	s_cselect_b32 s19, s40, 0x9148000
	s_cmp_lg_u32 s20, 0
	s_cselect_b32 s19, s19, 0x6148000
	s_cmp_eq_u32 s18, 1
	s_cselect_b32 s40, s40, 0x9148000
	s_add_u32 s57, s12, s19
	s_addc_u32 s58, s13, 0
	s_lshl_b32 s41, s20, 20
	s_or_b32 s41, s41, s43
	s_add_u32 s59, s65, s41
	s_addc_u32 s62, s4, 0
	s_add_u32 s63, s12, s40
	s_addc_u32 s66, s13, 0
	s_lshl_b32 s18, s18, 20
	s_or_b32 s18, s18, s43
	v_mov_b32_e32 v0, v166
	s_add_u32 s70, s65, s18
	s_addc_u32 s84, s4, 0
	v_readfirstlane_b32 s67, v0
	v_and_b32_e32 v2, 15, v0
	v_lshlrev_b32_e32 v132, 2, v0
	s_ashr_i32 s18, s67, 6
	v_and_b32_e32 v3, 48, v0
	v_lshlrev_b32_e32 v2, 6, v2
	v_and_b32_e32 v132, 32, v132
	s_lshl_b32 s85, s18, 10
	s_lshl_b32 s40, s67, 5
	v_bitop3_b32 v2, v2, v132, v3 bitop3:0x36
	s_lshl_b32 s18, s18, 12
	v_ashrrev_i32_e32 v3, 31, v0
	s_and_b32 s40, s40, 0xffffe000
	s_and_b32 s18, s18, 0x3000
	v_lshrrev_b32_e32 v3, 26, v3
	v_or_b32_e32 v144, s40, v2
	v_or_b32_e32 v143, s18, v2
	v_lshlrev_b32_e32 v2, 4, v0
	v_add_u32_e32 v138, v0, v3
	v_bfe_i32 v0, v0, 27, 1
	v_lshrrev_b32_e32 v0, 22, v0
	v_add_u32_e32 v0, v2, v0
	v_and_b32_e32 v0, 0xfffffc00, v0
	v_sub_u32_e32 v0, v2, v0
	v_lshrrev_b32_e32 v3, 4, v0
	v_bitop3_b32 v3, v3, v0, 32 bitop3:0x6c
	v_ashrrev_i32_e32 v0, 31, v0
	v_lshrrev_b32_e32 v0, 26, v0
	v_add_u32_e32 v0, v3, v0
	v_ashrrev_i32_e32 v145, 6, v0
	v_mul_i32_i24_e32 v133, 64, v145
	v_sub_u32_e32 v3, v3, v133
	v_ashrrev_i16_sdwa v3, v171, sext(v3) dst_sel:DWORD dst_unused:UNUSED_PAD src0_sel:DWORD src1_sel:BYTE_0
	v_add_u32_e32 v2, 0x2000, v2
	v_bfe_i32 v146, v3, 0, 16
	v_ashrrev_i32_e32 v3, 31, v2
	v_lshrrev_b32_e32 v3, 22, v3
	v_add_u32_e32 v3, v2, v3
	v_ashrrev_i32_e32 v136, 10, v3
	v_mul_i32_i24_e32 v3, 0x400, v136
	v_sub_u32_e32 v2, v2, v3
	v_lshrrev_b32_e32 v3, 4, v2
	v_bitop3_b32 v2, v3, v2, 32 bitop3:0x6c
	v_ashrrev_i32_e32 v133, 31, v2
	v_ashrrev_i32_e32 v139, 6, v138
	v_lshrrev_b32_e32 v133, 26, v133
	v_lshlrev_b32_e32 v132, 3, v139
	v_add_u32_e32 v133, v2, v133
	v_and_b32_e32 v132, -16, v132
	v_lshlrev_b32_e32 v0, 5, v139
	v_ashrrev_i32_e32 v137, 6, v133
	v_and_b32_e32 v133, 0xc0, v133
	v_add_u32_e32 v132, v145, v132
	v_and_b32_e32 v0, 32, v0
	v_lshlrev_b32_e32 v3, 3, v136
	v_sub_u32_e32 v2, v2, v133
	v_and_b32_e32 v3, -16, v3
	v_lshlrev_b32_e32 v134, 5, v136
	v_ashrrev_i16_sdwa v2, v171, sext(v2) dst_sel:DWORD dst_unused:UNUSED_PAD src0_sel:DWORD src1_sel:BYTE_0
	v_add_lshl_u32 v133, v0, v146, 1
	v_lshlrev_b32_e32 v135, 1, v132
	v_lshrrev_b32_e32 v148, 2, v132
	v_and_b32_e32 v149, 3, v145
	s_mov_b32 s18, 0x3fffe0
	v_add_u32_e32 v3, v137, v3
	v_and_b32_e32 v134, 32, v134
	v_bfe_i32 v147, v2, 0, 16
	v_lshl_add_u32 v0, v132, 10, v133
	v_and_b32_e32 v135, 24, v135
	v_and_b32_e32 v148, 4, v148
	v_and_or_b32 v132, v132, s18, v149
	v_add_lshl_u32 v134, v134, v147, 1
	v_or3_b32 v132, v132, v148, v135
	v_lshlrev_b32_e32 v135, 1, v3
	v_lshrrev_b32_e32 v148, 2, v3
	v_and_b32_e32 v149, 3, v137
	v_lshl_add_u32 v2, v3, 10, v134
	v_and_b32_e32 v135, 24, v135
	v_and_b32_e32 v148, 4, v148
	v_and_or_b32 v3, v3, s18, v149
	v_or3_b32 v135, v3, v148, v135
	v_lshlrev_b32_e32 v148, 13, v136
	v_lshlrev_b32_e32 v139, 13, v139
	v_and_b32_e32 v148, 0xffffc000, v148
	v_and_b32_e32 v139, 0xffffc000, v139
	v_lshl_add_u32 v137, v137, 10, v148
	v_lshlrev_b32_e32 v136, 6, v136
	v_lshl_add_u32 v139, v145, 10, v139
	s_add_u32 s18, s16, s19
	v_and_or_b32 v136, v136, 64, v137
	v_and_or_b32 v138, v138, 64, v139
	s_addc_u32 s19, s17, 0
	v_lshl_add_u32 v136, v147, 1, v136
	v_mov_b32_e32 v137, v1
	v_lshl_add_u32 v138, v146, 1, v138
	v_mov_b32_e32 v139, v1
	v_mov_b32_e32 v3, v1
	v_lshl_add_u32 v132, v132, 10, v133
	v_lshl_add_u32 v134, v135, 10, v134
	v_mov_b32_e32 v133, v1
	v_mov_b32_e32 v135, v1
	v_lshl_add_u64 v[136:137], s[18:19], 0, v[136:137]
	v_lshl_add_u64 v[138:139], s[18:19], 0, v[138:139]
	s_mov_b32 s86, -2
	s_mov_b64 s[40:41], 0x100
	v_add_u32_e32 v144, 0, v144
	.p2align	6

.LBB0_464:
	v_and_b32_e32 v19, 15, v18
	s_waitcnt vmcnt(0)
	v_and_b32_e32 v20, 48, v18
	v_lshlrev_b32_e32 v18, 2, v18
	s_and_b32 s16, s28, 0xffffff00
	v_lshlrev_b32_e32 v19, 6, v19
	v_and_b32_e32 v18, 32, v18
	s_lshl_b32 s12, s12, 12
	s_ashr_i32 s17, s16, 31
	v_or_b32_e32 v21, v19, v20
	s_lshl_b32 s13, s13, 13
	v_bitop3_b32 v19, v19, v18, v20 bitop3:0x36
	s_and_b32 s12, s12, 0x3000
	v_lshl_add_u64 v[8:9], v[8:9], 0, s[24:25]
	s_add_i32 m0, s6, 0x18000
	s_lshl_b64 s[16:17], s[16:17], 10
	v_bitop3_b32 v18, v21, s13, v18 bitop3:0xde
	v_or_b32_e32 v141, s12, v19
	s_waitcnt vmcnt(2)
	s_barrier
	global_load_lds_dwordx4 v[8:9], off
	v_lshl_add_u64 v[6:7], v[6:7], 0, s[24:25]
	s_add_i32 m0, s6, 0x1a000
	s_add_i32 s12, s6, 0x8000
	s_add_i32 s13, s6, 0xa000
	global_load_lds_dwordx4 v[6:7], off
	v_lshl_add_u64 v[4:5], v[4:5], 0, s[24:25]
	s_mov_b32 m0, s12
	s_add_u32 s18, s8, 0x20080
	global_load_lds_dwordx4 v[4:5], off
	v_lshl_add_u64 v[2:3], v[2:3], 0, s[24:25]
	s_mov_b32 m0, s13
	s_addc_u32 s19, s9, 0
	global_load_lds_dwordx4 v[2:3], off
	v_lshl_add_u64 v[2:3], s[18:19], 0, v[0:1]
	s_add_i32 m0, s6, 0x1c000
	v_add_u32_e32 v142, 0, v18
	global_load_lds_dwordx4 v[2:3], off
	v_lshl_add_u64 v[2:3], s[18:19], 0, v[134:135]
	s_add_i32 m0, s6, 0x1e000
	s_add_u32 s16, s72, s16
	global_load_lds_dwordx4 v[2:3], off
	v_lshlrev_b32_e32 v2, 12, v14
	v_and_b32_e32 v2, 0x7fffe000, v2
	v_lshl_add_u32 v2, v15, 9, v2
	v_or_b32_e32 v2, v2, v16
	v_add_lshl_u32 v2, v2, v17, 1
	v_mov_b32_e32 v3, v1
	s_addc_u32 s17, s73, s17
	v_lshl_add_u64 v[136:137], s[16:17], 0, v[2:3]
	v_lshlrev_b32_e32 v2, 12, v10
	v_and_b32_e32 v2, 0x7fffe000, v2
	v_lshl_add_u32 v2, v11, 9, v2
	v_or_b32_e32 v2, v2, v12
	s_waitcnt vmcnt(6)
	v_add_lshl_u32 v2, v2, v13, 1
	v_lshl_add_u64 v[138:139], s[16:17], 0, v[2:3]
	v_mov_b32_e32 v2, 0
	s_mov_b32 s16, -2
	s_mov_b64 s[18:19], 0xea68080
	v_mov_b32_e32 v3, v2
	v_mov_b32_e32 v4, v2
	v_mov_b32_e32 v5, v2
	v_mov_b32_e32 v6, v2
	v_mov_b32_e32 v7, v2
	v_mov_b32_e32 v8, v2
	v_mov_b32_e32 v9, v2
	v_mov_b32_e32 v18, v2
	v_mov_b32_e32 v19, v2
	v_mov_b32_e32 v20, v2
	v_mov_b32_e32 v21, v2
	v_mov_b32_e32 v22, v2
	v_mov_b32_e32 v23, v2
	v_mov_b32_e32 v24, v2
	v_mov_b32_e32 v25, v2
	v_mov_b32_e32 v34, v2
	v_mov_b32_e32 v35, v2
	v_mov_b32_e32 v36, v2
	v_mov_b32_e32 v37, v2
	v_mov_b32_e32 v38, v2
	v_mov_b32_e32 v39, v2
	v_mov_b32_e32 v40, v2
	v_mov_b32_e32 v41, v2
	v_mov_b32_e32 v50, v2
	v_mov_b32_e32 v51, v2
	v_mov_b32_e32 v52, v2
	v_mov_b32_e32 v53, v2
	v_mov_b32_e32 v54, v2
	v_mov_b32_e32 v55, v2
	v_mov_b32_e32 v56, v2
	v_mov_b32_e32 v57, v2
	v_mov_b32_e32 v10, v2
	v_mov_b32_e32 v11, v2
	v_mov_b32_e32 v12, v2
	v_mov_b32_e32 v13, v2
	v_mov_b32_e32 v14, v2
	v_mov_b32_e32 v15, v2
	v_mov_b32_e32 v16, v2
	v_mov_b32_e32 v17, v2
	v_mov_b32_e32 v26, v2
	v_mov_b32_e32 v27, v2
	v_mov_b32_e32 v28, v2
	v_mov_b32_e32 v29, v2
	v_mov_b32_e32 v30, v2
	v_mov_b32_e32 v31, v2
	v_mov_b32_e32 v32, v2
	v_mov_b32_e32 v33, v2
	v_mov_b32_e32 v42, v2
	v_mov_b32_e32 v43, v2
	v_mov_b32_e32 v44, v2
	v_mov_b32_e32 v45, v2
	v_mov_b32_e32 v46, v2
	v_mov_b32_e32 v47, v2
	v_mov_b32_e32 v48, v2
	v_mov_b32_e32 v49, v2
	v_mov_b32_e32 v58, v2
	v_mov_b32_e32 v59, v2
	v_mov_b32_e32 v60, v2
	v_mov_b32_e32 v61, v2
	v_mov_b32_e32 v62, v2
	v_mov_b32_e32 v63, v2
	v_mov_b32_e32 v64, v2
	v_mov_b32_e32 v65, v2
	v_mov_b32_e32 v66, v2
	v_mov_b32_e32 v67, v2
	v_mov_b32_e32 v68, v2
	v_mov_b32_e32 v69, v2
	v_mov_b32_e32 v70, v2
	v_mov_b32_e32 v71, v2
	v_mov_b32_e32 v72, v2
	v_mov_b32_e32 v73, v2
	v_mov_b32_e32 v82, v2
	v_mov_b32_e32 v83, v2
	v_mov_b32_e32 v84, v2
	v_mov_b32_e32 v85, v2
	v_mov_b32_e32 v86, v2
	v_mov_b32_e32 v87, v2
	v_mov_b32_e32 v88, v2
	v_mov_b32_e32 v89, v2
	v_mov_b32_e32 v98, v2
	v_mov_b32_e32 v99, v2
	v_mov_b32_e32 v100, v2
	v_mov_b32_e32 v101, v2
	v_mov_b32_e32 v102, v2
	v_mov_b32_e32 v103, v2
	v_mov_b32_e32 v104, v2
	v_mov_b32_e32 v105, v2
	v_mov_b32_e32 v114, v2
	v_mov_b32_e32 v115, v2
	v_mov_b32_e32 v116, v2
	v_mov_b32_e32 v117, v2
	v_mov_b32_e32 v118, v2
	v_mov_b32_e32 v119, v2
	v_mov_b32_e32 v120, v2
	v_mov_b32_e32 v121, v2
	v_mov_b32_e32 v74, v2
	v_mov_b32_e32 v75, v2
	v_mov_b32_e32 v76, v2
	v_mov_b32_e32 v77, v2
	v_mov_b32_e32 v78, v2
	v_mov_b32_e32 v79, v2
	v_mov_b32_e32 v80, v2
	v_mov_b32_e32 v81, v2
	v_mov_b32_e32 v90, v2
	v_mov_b32_e32 v91, v2
	v_mov_b32_e32 v92, v2
	v_mov_b32_e32 v93, v2
	v_mov_b32_e32 v94, v2
	v_mov_b32_e32 v95, v2
	v_mov_b32_e32 v96, v2
	v_mov_b32_e32 v97, v2
	v_mov_b32_e32 v106, v2
	v_mov_b32_e32 v107, v2
	v_mov_b32_e32 v108, v2
	v_mov_b32_e32 v109, v2
	v_mov_b32_e32 v110, v2
	v_mov_b32_e32 v111, v2
	v_mov_b32_e32 v112, v2
	v_mov_b32_e32 v113, v2
	v_mov_b32_e32 v122, v2
	v_mov_b32_e32 v123, v2
	v_mov_b32_e32 v124, v2
	v_mov_b32_e32 v125, v2
	v_mov_b32_e32 v126, v2
	v_mov_b32_e32 v127, v2
	v_mov_b32_e32 v128, v2
	v_mov_b32_e32 v129, v2
	s_barrier
	.p2align	6

.LBB0_475:
	v_and_b32_e32 v3, 15, v2
	v_and_b32_e32 v8, 48, v2
	v_lshlrev_b32_e32 v2, 2, v2
	v_lshlrev_b32_e32 v3, 6, v3
	v_and_b32_e32 v2, 32, v2
	s_lshl_b32 s4, s4, 12
	v_lshl_add_u64 v[138:139], s[40:41], 0, v[0:1]
	v_mov_b32_e32 v39, v1
	v_or_b32_e32 v9, v3, v8
	s_lshl_b32 s5, s5, 13
	v_bitop3_b32 v3, v3, v2, v8 bitop3:0x36
	s_and_b32 s4, s4, 0x3000
	v_lshl_add_u64 v[40:41], s[40:41], 0, v[38:39]
	v_mov_b32_e32 v27, v1
	v_bitop3_b32 v8, v9, s5, v2 bitop3:0xde
	v_or_b32_e32 v140, s4, v3
	v_lshl_add_u64 v[2:3], v[138:139], 0, s[24:25]
	s_add_i32 m0, s12, 0x18000
	v_lshl_add_u64 v[4:5], s[2:3], 0, v[26:27]
	v_mov_b32_e32 v29, v1
	s_waitcnt vmcnt(2)
	s_barrier
	global_load_lds_dwordx4 v[2:3], off
	v_lshl_add_u64 v[2:3], v[40:41], 0, s[24:25]
	s_add_i32 m0, s12, 0x1a000
	s_add_i32 s19, s12, 0x8000
	s_add_i32 s62, s12, 0xa000
	v_lshl_add_u64 v[6:7], s[2:3], 0, v[28:29]
	global_load_lds_dwordx4 v[2:3], off
	v_lshl_add_u64 v[2:3], v[4:5], 0, s[24:25]
	s_mov_b32 m0, s19
	s_add_u32 s4, s40, 0x20080
	global_load_lds_dwordx4 v[2:3], off
	v_lshl_add_u64 v[2:3], v[6:7], 0, s[24:25]
	s_mov_b32 m0, s62
	s_addc_u32 s5, s41, 0
	global_load_lds_dwordx4 v[2:3], off
	v_lshl_add_u64 v[2:3], s[4:5], 0, v[0:1]
	s_add_i32 m0, s12, 0x1c000
	s_mov_b32 s20, 0
	global_load_lds_dwordx4 v[2:3], off
	v_lshl_add_u64 v[2:3], s[4:5], 0, v[38:39]
	s_add_i32 m0, s12, 0x1e000
	s_mov_b64 s[44:45], -1
	global_load_lds_dwordx4 v[2:3], off
	s_waitcnt vmcnt(6)
	v_mov_b32_e32 v2, 0
	s_mov_b64 s[46:47], 0
	v_add_u32_e32 v141, 0, v8
	v_mov_b32_e32 v3, v2
	v_mov_b32_e32 v4, v2
	v_mov_b32_e32 v5, v2
	v_mov_b32_e32 v6, v2
	v_mov_b32_e32 v7, v2
	v_mov_b32_e32 v8, v2
	v_mov_b32_e32 v9, v2
	v_mov_b32_e32 v18, v2
	v_mov_b32_e32 v19, v2
	v_mov_b32_e32 v20, v2
	v_mov_b32_e32 v21, v2
	v_mov_b32_e32 v22, v2
	v_mov_b32_e32 v23, v2
	v_mov_b32_e32 v24, v2
	v_mov_b32_e32 v25, v2
	v_mov_b32_e32 v42, v2
	v_mov_b32_e32 v43, v2
	v_mov_b32_e32 v44, v2
	v_mov_b32_e32 v45, v2
	v_mov_b32_e32 v46, v2
	v_mov_b32_e32 v47, v2
	v_mov_b32_e32 v48, v2
	v_mov_b32_e32 v49, v2
	v_mov_b32_e32 v58, v2
	v_mov_b32_e32 v59, v2
	v_mov_b32_e32 v60, v2
	v_mov_b32_e32 v61, v2
	v_mov_b32_e32 v62, v2
	v_mov_b32_e32 v63, v2
	v_mov_b32_e32 v64, v2
	v_mov_b32_e32 v65, v2
	v_mov_b32_e32 v10, v2
	v_mov_b32_e32 v11, v2
	v_mov_b32_e32 v12, v2
	v_mov_b32_e32 v13, v2
	v_mov_b32_e32 v14, v2
	v_mov_b32_e32 v15, v2
	v_mov_b32_e32 v16, v2
	v_mov_b32_e32 v17, v2
	v_mov_b32_e32 v30, v2
	v_mov_b32_e32 v31, v2
	v_mov_b32_e32 v32, v2
	v_mov_b32_e32 v33, v2
	v_mov_b32_e32 v34, v2
	v_mov_b32_e32 v35, v2
	v_mov_b32_e32 v36, v2
	v_mov_b32_e32 v37, v2
	v_mov_b32_e32 v50, v2
	v_mov_b32_e32 v51, v2
	v_mov_b32_e32 v52, v2
	v_mov_b32_e32 v53, v2
	v_mov_b32_e32 v54, v2
	v_mov_b32_e32 v55, v2
	v_mov_b32_e32 v56, v2
	v_mov_b32_e32 v57, v2
	v_mov_b32_e32 v66, v2
	v_mov_b32_e32 v67, v2
	v_mov_b32_e32 v68, v2
	v_mov_b32_e32 v69, v2
	v_mov_b32_e32 v70, v2
	v_mov_b32_e32 v71, v2
	v_mov_b32_e32 v72, v2
	v_mov_b32_e32 v73, v2
	v_mov_b32_e32 v74, v2
	v_mov_b32_e32 v75, v2
	v_mov_b32_e32 v76, v2
	v_mov_b32_e32 v77, v2
	v_mov_b32_e32 v78, v2
	v_mov_b32_e32 v79, v2
	v_mov_b32_e32 v80, v2
	v_mov_b32_e32 v81, v2
	v_mov_b32_e32 v90, v2
	v_mov_b32_e32 v91, v2
	v_mov_b32_e32 v92, v2
	v_mov_b32_e32 v93, v2
	v_mov_b32_e32 v94, v2
	v_mov_b32_e32 v95, v2
	v_mov_b32_e32 v96, v2
	v_mov_b32_e32 v97, v2
	v_mov_b32_e32 v106, v2
	v_mov_b32_e32 v107, v2
	v_mov_b32_e32 v108, v2
	v_mov_b32_e32 v109, v2
	v_mov_b32_e32 v110, v2
	v_mov_b32_e32 v111, v2
	v_mov_b32_e32 v112, v2
	v_mov_b32_e32 v113, v2
	v_mov_b32_e32 v122, v2
	v_mov_b32_e32 v123, v2
	v_mov_b32_e32 v124, v2
	v_mov_b32_e32 v125, v2
	v_mov_b32_e32 v126, v2
	v_mov_b32_e32 v127, v2
	v_mov_b32_e32 v128, v2
	v_mov_b32_e32 v129, v2
	v_mov_b32_e32 v82, v2
	v_mov_b32_e32 v83, v2
	v_mov_b32_e32 v84, v2
	v_mov_b32_e32 v85, v2
	v_mov_b32_e32 v86, v2
	v_mov_b32_e32 v87, v2
	v_mov_b32_e32 v88, v2
	v_mov_b32_e32 v89, v2
	v_mov_b32_e32 v98, v2
	v_mov_b32_e32 v99, v2
	v_mov_b32_e32 v100, v2
	v_mov_b32_e32 v101, v2
	v_mov_b32_e32 v102, v2
	v_mov_b32_e32 v103, v2
	v_mov_b32_e32 v104, v2
	v_mov_b32_e32 v105, v2
	v_mov_b32_e32 v114, v2
	v_mov_b32_e32 v115, v2
	v_mov_b32_e32 v116, v2
	v_mov_b32_e32 v117, v2
	v_mov_b32_e32 v118, v2
	v_mov_b32_e32 v119, v2
	v_mov_b32_e32 v120, v2
	v_mov_b32_e32 v121, v2
	v_mov_b32_e32 v130, v2
	v_mov_b32_e32 v131, v2
	v_mov_b32_e32 v132, v2
	v_mov_b32_e32 v133, v2
	v_mov_b32_e32 v134, v2
	v_mov_b32_e32 v135, v2
	v_mov_b32_e32 v136, v2
	v_mov_b32_e32 v137, v2
	s_barrier
	.p2align	6

.LBB0_481:
	s_lshl_b32 s17, s17, 12
	v_lshl_add_u64 v[138:139], v[138:139], 0, s[44:45]
	s_add_i32 m0, s11, 0x18000
	s_lshl_b32 s20, s19, 13
	s_and_b32 s46, s17, 0x3000
	s_waitcnt vmcnt(2)
	s_barrier
	global_load_lds_dwordx4 v[138:139], off
	v_lshl_add_u64 v[40:41], v[40:41], 0, s[44:45]
	s_add_i32 m0, s11, 0x1a000
	s_add_i32 s17, s11, 0x8000
	s_add_i32 s19, s11, 0xa000
	global_load_lds_dwordx4 v[40:41], off
	v_lshl_add_u64 v[40:41], v[142:143], 0, s[24:25]
	s_mov_b32 m0, s17
	s_add_u32 s44, s40, 0x20280
	global_load_lds_dwordx4 v[40:41], off
	v_lshl_add_u64 v[40:41], v[140:141], 0, s[24:25]
	s_mov_b32 m0, s19
	s_addc_u32 s45, s41, 0
	global_load_lds_dwordx4 v[40:41], off
	v_lshl_add_u64 v[40:41], s[44:45], 0, v[0:1]
	s_add_i32 m0, s11, 0x1c000
	v_lshlrev_b32_e32 v139, 2, v145
	global_load_lds_dwordx4 v[40:41], off
	v_lshl_add_u64 v[40:41], s[44:45], 0, v[38:39]
	s_add_i32 m0, s11, 0x1e000
	v_and_b32_e32 v139, 32, v139
	global_load_lds_dwordx4 v[40:41], off
	v_and_b32_e32 v40, 15, v145
	v_and_b32_e32 v41, 48, v145
	v_lshlrev_b32_e32 v40, 6, v40
	v_or_b32_e32 v138, v40, v41
	s_waitcnt vmcnt(6)
	v_bitop3_b32 v40, v40, v139, v41 bitop3:0x36
	v_bitop3_b32 v41, v138, s20, v139 bitop3:0xde
	v_or_b32_e32 v40, s46, v40
	s_mov_b32 s20, 0
	s_mov_b64 s[44:45], -1
	s_mov_b64 s[46:47], 0
	v_add_u32_e32 v41, 0, v41
	s_barrier
	.p2align	6

.LBB0_1016:
	s_andn2_b64 vcc, exec, s[2:3]
	s_cbranch_vccnz .LBB0_1201
	v_lshl_add_u64 v[160:161], s[0:1], 0, v[0:1]
	v_lshl_add_u64 v[162:163], v[2:3], 0, v[0:1]
	v_or_b32_e32 v0, v39, v38
	v_and_b32_e32 v2, 15, v41
	v_sub_u32_e64 v3, v0, 8 clamp
	v_lshlrev_b32_e32 v202, 7, v2
	v_mul_u32_u24_e32 v205, 0x90, v2
	v_sub_u32_e32 v2, v198, v0
	v_min_u32_e32 v3, 48, v3
	v_max_i32_e32 v207, -15, v2
	v_or_b32_e32 v2, 1, v198
	v_cmp_ge_u32_e64 s[42:43], v2, v3
	v_sub_u32_e32 v2, v2, v0
	v_max_i32_e32 v208, -15, v2
	v_or_b32_e32 v2, 2, v198
	v_cmp_ge_u32_e64 s[44:45], v2, v3
	v_sub_u32_e32 v2, v2, v0
	v_max_i32_e32 v209, -15, v2
	v_or_b32_e32 v2, 3, v198
	v_cmp_ge_u32_e64 s[46:47], v2, v3
	v_sub_u32_e32 v2, v2, v0
	v_max_i32_e32 v210, -15, v2
	v_or_b32_e32 v2, 16, v198
	v_max_i32_e32 v38, 3, v37
	v_cmp_ge_u32_e32 vcc, v2, v3
	v_sub_u32_e32 v2, v2, v0
	v_add_u32_e32 v38, -3, v38
	v_max_i32_e32 v2, -15, v2
	v_min_u32_e32 v38, 24, v38
	v_add_u32_e32 v2, 15, v2
	v_add_u32_e32 v201, 8, v38
	v_add_u32_e32 v38, 16, v3
	v_cmp_lt_u32_e64 s[0:1], v198, v3
	v_min_u32_e32 v211, 30, v2
	v_or_b32_e32 v2, 17, v198
	s_and_b64 s[90:91], vcc, s[0:1]
	v_cmp_ge_u32_e32 vcc, v2, v3
	v_cmp_lt_u32_e64 s[0:1], v2, v38
	v_sub_u32_e32 v2, v2, v0
	v_max_i32_e32 v2, -15, v2
	v_add_u32_e32 v2, 15, v2
	v_min_u32_e32 v212, 30, v2
	v_or_b32_e32 v2, 18, v198
	s_add_i32 s28, s8, 16
	s_and_b64 s[8:9], vcc, s[0:1]
	v_cmp_ge_u32_e32 vcc, v2, v3
	v_cmp_lt_u32_e64 s[0:1], v2, v38
	v_sub_u32_e32 v2, v2, v0
	v_max_i32_e32 v2, -15, v2
	v_add_u32_e32 v2, 15, v2
	v_min_u32_e32 v213, 30, v2
	v_or_b32_e32 v2, 19, v198
	s_and_b64 s[88:89], vcc, s[0:1]
	v_cmp_ge_u32_e32 vcc, v2, v3
	v_cmp_lt_u32_e64 s[0:1], v2, v38
	v_sub_u32_e32 v2, v2, v0
	v_max_i32_e32 v2, -15, v2
	v_add_u32_e32 v2, 15, v2
	v_min_u32_e32 v214, 30, v2
	v_or_b32_e32 v2, 32, v198
	s_and_b64 s[94:95], vcc, s[0:1]
	v_cmp_ge_u32_e32 vcc, v2, v3
	v_cmp_lt_u32_e64 s[0:1], v2, v38
	v_sub_u32_e32 v2, v2, v0
	v_max_i32_e32 v2, -15, v2
	v_add_u32_e32 v2, 15, v2
	v_min_u32_e32 v215, 30, v2
	v_or_b32_e32 v2, 33, v198
	s_and_b64 s[96:97], vcc, s[0:1]
	v_cmp_ge_u32_e32 vcc, v2, v3
	v_cmp_lt_u32_e64 s[0:1], v2, v38
	v_sub_u32_e32 v2, v2, v0
	v_max_i32_e32 v2, -15, v2
	v_add_u32_e32 v2, 15, v2
	v_min_u32_e32 v216, 30, v2
	v_or_b32_e32 v2, 34, v198
	s_and_b64 s[84:85], vcc, s[0:1]
	v_cmp_ge_u32_e32 vcc, v2, v3
	v_cmp_lt_u32_e64 s[0:1], v2, v38
	v_sub_u32_e32 v2, v2, v0
	v_max_i32_e32 v2, -15, v2
	v_add_u32_e32 v2, 15, v2
	v_min_u32_e32 v217, 30, v2
	v_or_b32_e32 v2, 35, v198
	s_and_b64 s[18:19], vcc, s[0:1]
	v_cmp_ge_u32_e32 vcc, v2, v3
	v_cmp_lt_u32_e64 s[0:1], v2, v38
	v_sub_u32_e32 v2, v2, v0
	v_max_i32_e32 v2, -15, v2
	v_add_u32_e32 v2, 15, v2
	v_min_u32_e32 v218, 30, v2
	v_or_b32_e32 v2, 48, v198
	v_cmp_lt_u32_e64 s[48:49], v2, v38
	v_sub_u32_e32 v2, v2, v0
	v_add_u32_e32 v2, 15, v2
	v_min_u32_e32 v219, 30, v2
	v_or_b32_e32 v2, 49, v198
	v_cmp_lt_u32_e64 s[50:51], v2, v38
	v_sub_u32_e32 v2, v2, v0
	v_add_u32_e32 v2, 15, v2
	v_min_u32_e32 v220, 30, v2
	v_or_b32_e32 v2, 50, v198
	v_cmp_lt_u32_e64 s[52:53], v2, v38
	v_sub_u32_e32 v2, v2, v0
	v_add_u32_e32 v2, 15, v2
	v_min_u32_e32 v221, 30, v2
	v_or_b32_e32 v2, 51, v198
	v_sub_u32_e32 v0, v2, v0
	v_add_u32_e32 v0, 15, v0
	v_min_u32_e32 v222, 30, v0
	v_or_b32_e32 v0, 1, v37
	s_and_b32 s2, s12, 28
	v_max_i32_e32 v0, 4, v0
	v_max_i32_e32 v43, 4, v37
	s_max_u32 s4, s2, 4
	v_xor_b32_e32 v39, v40, v42
	v_add_u32_e32 v0, -4, v0
	v_add_u32_e32 v43, -4, v43
	v_lshlrev_b32_e32 v203, 4, v39
	v_bitop3_b32 v39, v40, v42, 4 bitop3:0x36
	v_cmp_ge_u32_e64 s[40:41], v198, v3
	v_cmp_lt_u32_e64 s[54:55], v2, v38
	v_min_u32_e32 v223, 24, v0
	v_sub_u32_e32 v0, s4, v36
	v_mov_b32_e32 v2, v1
	v_mov_b32_e32 v3, v1
	v_lshlrev_b32_e32 v199, 3, v40
	v_min_u32_e32 v200, 24, v43
	v_lshlrev_b32_e32 v204, 4, v39
	v_subrev_u32_e32 v225, s2, v0
	v_mov_b32_e32 v157, v156
	v_mov_b32_e32 v0, v1
	v_mov_b32_e32 v68, 0
	v_mov_b64_e32 v[38:39], v[2:3]
	v_mov_b64_e32 v[54:55], v[2:3]
	v_mov_b64_e32 v[42:43], v[2:3]
	v_mov_b64_e32 v[62:63], v[2:3]
	v_mov_b64_e32 v[46:47], v[2:3]
	v_mov_b64_e32 v[66:67], v[2:3]
	v_mov_b64_e32 v[50:51], v[2:3]
	v_mov_b64_e32 v[74:75], v[2:3]
	v_add_u32_e32 v206, 8, v200
	s_and_b64 s[62:63], vcc, s[0:1]
	v_add_u32_e32 v224, 8, v223
	s_mov_b32 s5, 0
	s_movk_i32 s70, 0xc0
	v_mov_b64_e32 v[36:37], v[0:1]
	v_mov_b64_e32 v[52:53], v[0:1]
	v_mov_b64_e32 v[40:41], v[0:1]
	v_mov_b64_e32 v[60:61], v[0:1]
	v_mov_b64_e32 v[44:45], v[0:1]
	v_mov_b64_e32 v[64:65], v[0:1]
	v_mov_b64_e32 v[48:49], v[0:1]
	v_mov_b64_e32 v[72:73], v[0:1]
	s_mov_b32 s0, 0
	v_mov_b64_e32 v[2:3], v[156:157]
	v_mov_b32_e32 v69, v68
	v_mov_b32_e32 v70, v68
	v_mov_b32_e32 v71, v68
	v_mov_b32_e32 v56, v68
	v_mov_b32_e32 v57, v68
	v_mov_b32_e32 v58, v68
	v_mov_b32_e32 v59, v68
	.p2align	6

.LBB0_1253:
	v_and_b32_e32 v3, 15, v2
	v_and_b32_e32 v12, 48, v2
	v_lshlrev_b32_e32 v2, 2, v2
	v_lshlrev_b32_e32 v3, 6, v3
	v_and_b32_e32 v2, 32, v2
	s_lshl_b32 s17, s17, 12
	v_lshl_add_u64 v[4:5], s[8:9], 0, v[0:1]
	v_mov_b32_e32 v135, v1
	v_or_b32_e32 v13, v3, v12
	s_lshl_b32 s20, s20, 13
	v_bitop3_b32 v3, v3, v2, v12 bitop3:0x36
	s_and_b32 s17, s17, 0x3000
	v_lshl_add_u64 v[6:7], s[8:9], 0, v[134:135]
	v_mov_b32_e32 v131, v1
	v_bitop3_b32 v12, v13, s20, v2 bitop3:0xde
	v_or_b32_e32 v137, s17, v3
	v_lshl_add_u64 v[2:3], v[4:5], 0, s[24:25]
	s_add_i32 m0, s11, 0x18000
	v_lshl_add_u64 v[8:9], s[2:3], 0, v[130:131]
	v_mov_b32_e32 v133, v1
	s_waitcnt vmcnt(2)
	s_barrier
	global_load_lds_dwordx4 v[2:3], off
	v_lshl_add_u64 v[2:3], v[6:7], 0, s[24:25]
	s_add_i32 m0, s11, 0x1a000
	s_add_i32 s17, s11, 0x8000
	s_add_i32 s28, s11, 0xa000
	v_lshl_add_u64 v[10:11], s[2:3], 0, v[132:133]
	global_load_lds_dwordx4 v[2:3], off
	v_lshl_add_u64 v[2:3], v[8:9], 0, s[24:25]
	s_mov_b32 m0, s17
	s_add_u32 s40, s8, 0x10080
	global_load_lds_dwordx4 v[2:3], off
	v_lshl_add_u64 v[2:3], v[10:11], 0, s[24:25]
	s_mov_b32 m0, s28
	s_addc_u32 s41, s9, 0
	global_load_lds_dwordx4 v[2:3], off
	v_lshl_add_u64 v[2:3], s[40:41], 0, v[0:1]
	s_add_i32 m0, s11, 0x1c000
	s_mov_b32 s20, 0
	global_load_lds_dwordx4 v[2:3], off
	v_lshl_add_u64 v[2:3], s[40:41], 0, v[134:135]
	s_add_i32 m0, s11, 0x1e000
	s_mov_b64 s[40:41], -1
	global_load_lds_dwordx4 v[2:3], off
	s_waitcnt vmcnt(6)
	v_mov_b32_e32 v2, 0
	s_mov_b64 s[42:43], 0
	v_add_u32_e32 v138, 0, v12
	v_mov_b32_e32 v3, v2
	v_mov_b32_e32 v4, v2
	v_mov_b32_e32 v5, v2
	v_mov_b32_e32 v6, v2
	v_mov_b32_e32 v7, v2
	v_mov_b32_e32 v8, v2
	v_mov_b32_e32 v9, v2
	v_mov_b32_e32 v10, v2
	v_mov_b32_e32 v11, v2
	v_mov_b32_e32 v12, v2
	v_mov_b32_e32 v13, v2
	v_mov_b32_e32 v14, v2
	v_mov_b32_e32 v15, v2
	v_mov_b32_e32 v16, v2
	v_mov_b32_e32 v17, v2
	s_waitcnt vmcnt(0)
	v_mov_b32_e32 v26, v2
	v_mov_b32_e32 v27, v2
	v_mov_b32_e32 v28, v2
	v_mov_b32_e32 v29, v2
	v_mov_b32_e32 v30, v2
	v_mov_b32_e32 v31, v2
	v_mov_b32_e32 v32, v2
	v_mov_b32_e32 v33, v2
	v_mov_b32_e32 v42, v2
	v_mov_b32_e32 v43, v2
	v_mov_b32_e32 v44, v2
	v_mov_b32_e32 v45, v2
	v_mov_b32_e32 v46, v2
	v_mov_b32_e32 v47, v2
	v_mov_b32_e32 v48, v2
	v_mov_b32_e32 v49, v2
	v_mov_b32_e32 v18, v2
	v_mov_b32_e32 v19, v2
	v_mov_b32_e32 v20, v2
	v_mov_b32_e32 v21, v2
	v_mov_b32_e32 v22, v2
	v_mov_b32_e32 v23, v2
	v_mov_b32_e32 v24, v2
	v_mov_b32_e32 v25, v2
	v_mov_b32_e32 v34, v2
	v_mov_b32_e32 v35, v2
	v_mov_b32_e32 v36, v2
	v_mov_b32_e32 v37, v2
	v_mov_b32_e32 v38, v2
	v_mov_b32_e32 v39, v2
	v_mov_b32_e32 v40, v2
	v_mov_b32_e32 v41, v2
	v_mov_b32_e32 v50, v2
	v_mov_b32_e32 v51, v2
	v_mov_b32_e32 v52, v2
	v_mov_b32_e32 v53, v2
	v_mov_b32_e32 v54, v2
	v_mov_b32_e32 v55, v2
	v_mov_b32_e32 v56, v2
	v_mov_b32_e32 v57, v2
	v_mov_b32_e32 v58, v2
	v_mov_b32_e32 v59, v2
	v_mov_b32_e32 v60, v2
	v_mov_b32_e32 v61, v2
	v_mov_b32_e32 v62, v2
	v_mov_b32_e32 v63, v2
	v_mov_b32_e32 v64, v2
	v_mov_b32_e32 v65, v2
	v_mov_b32_e32 v66, v2
	v_mov_b32_e32 v67, v2
	v_mov_b32_e32 v68, v2
	v_mov_b32_e32 v69, v2
	v_mov_b32_e32 v70, v2
	v_mov_b32_e32 v71, v2
	v_mov_b32_e32 v72, v2
	v_mov_b32_e32 v73, v2
	v_mov_b32_e32 v74, v2
	v_mov_b32_e32 v75, v2
	v_mov_b32_e32 v76, v2
	v_mov_b32_e32 v77, v2
	v_mov_b32_e32 v78, v2
	v_mov_b32_e32 v79, v2
	v_mov_b32_e32 v80, v2
	v_mov_b32_e32 v81, v2
	v_mov_b32_e32 v90, v2
	v_mov_b32_e32 v91, v2
	v_mov_b32_e32 v92, v2
	v_mov_b32_e32 v93, v2
	v_mov_b32_e32 v94, v2
	v_mov_b32_e32 v95, v2
	v_mov_b32_e32 v96, v2
	v_mov_b32_e32 v97, v2
	v_mov_b32_e32 v106, v2
	v_mov_b32_e32 v107, v2
	v_mov_b32_e32 v108, v2
	v_mov_b32_e32 v109, v2
	v_mov_b32_e32 v110, v2
	v_mov_b32_e32 v111, v2
	v_mov_b32_e32 v112, v2
	v_mov_b32_e32 v113, v2
	v_mov_b32_e32 v82, v2
	v_mov_b32_e32 v83, v2
	v_mov_b32_e32 v84, v2
	v_mov_b32_e32 v85, v2
	v_mov_b32_e32 v86, v2
	v_mov_b32_e32 v87, v2
	v_mov_b32_e32 v88, v2
	v_mov_b32_e32 v89, v2
	v_mov_b32_e32 v98, v2
	v_mov_b32_e32 v99, v2
	v_mov_b32_e32 v100, v2
	v_mov_b32_e32 v101, v2
	v_mov_b32_e32 v102, v2
	v_mov_b32_e32 v103, v2
	v_mov_b32_e32 v104, v2
	v_mov_b32_e32 v105, v2
	v_mov_b32_e32 v114, v2
	v_mov_b32_e32 v115, v2
	v_mov_b32_e32 v116, v2
	v_mov_b32_e32 v117, v2
	v_mov_b32_e32 v118, v2
	v_mov_b32_e32 v119, v2
	v_mov_b32_e32 v120, v2
	v_mov_b32_e32 v121, v2
	v_mov_b32_e32 v122, v2
	v_mov_b32_e32 v123, v2
	v_mov_b32_e32 v124, v2
	v_mov_b32_e32 v125, v2
	v_mov_b32_e32 v126, v2
	v_mov_b32_e32 v127, v2
	v_mov_b32_e32 v128, v2
	v_mov_b32_e32 v129, v2
	s_barrier
	.p2align	6

.LBB0_1268:
	v_mov_b32_e32 v37, v166
	s_add_u32 s6, s72, s18
	v_ashrrev_i32_e32 v142, 3, v37
	v_bfe_u32 v40, v37, 4, 2
	v_ashrrev_i32_e32 v143, 31, v142
	s_addc_u32 s7, s73, s19
	v_lshlrev_b32_e32 v0, 4, v40
	v_and_b32_e32 v41, 7, v37
	v_lshlrev_b64 v[38:39], 7, v[142:143]
	s_add_u32 s6, s6, s8
	v_lshl_add_u64 v[2:3], v[140:141], 0, v[0:1]
	v_lshlrev_b32_e32 v0, 4, v41
	v_lshl_add_u64 v[4:5], s[2:3], 0, v[38:39]
	s_addc_u32 s7, s7, s9
	v_lshl_add_u64 v[8:9], v[4:5], 0, v[0:1]
	v_mad_i64_i32 v[10:11], s[10:11], s40, v142, 0
	global_load_dwordx4 v[4:7], v[8:9], off
	v_lshl_add_u64 v[10:11], v[10:11], 1, s[6:7]
	v_add_co_u32_e32 v8, vcc, s83, v8
	v_lshl_add_u64 v[144:145], v[10:11], 0, v[0:1]
	s_nop 0
	v_addc_co_u32_e32 v9, vcc, 0, v9, vcc
	global_load_dwordx4 v[32:35], v[144:145], off
	s_nop 0
	global_load_dwordx4 v[8:11], v[8:9], off
	s_nop 0
	global_load_dwordx4 v[20:23], v[144:145], off offset:128
	global_load_dwordx4 v[12:15], v[2:3], off
	global_load_dwordx4 v[16:19], v[2:3], off offset:64
	v_add_co_u32_e32 v2, vcc, s56, v2
	v_lshrrev_b32_e32 v42, 4, v37
	s_nop 0
	v_addc_co_u32_e32 v3, vcc, 0, v3, vcc
	global_load_dwordx4 v[24:27], v[2:3], off
	global_load_dwordx4 v[28:31], v[2:3], off offset:64
	v_and_b32_e32 v43, 15, v37
	v_xor_b32_e32 v37, v142, v37
	v_lshlrev_b32_e32 v44, 7, v142
	s_lshr_b32 s10, s5, 1
	v_lshlrev_b32_e32 v37, 4, v37
	s_movk_i32 s12, 0x70
	s_add_u32 s8, s8, s18
	v_and_or_b32 v162, v37, s12, v44
	s_movk_i32 s12, 0x90
	v_lshlrev_b32_e32 v146, 3, v40
	v_bitop3_b32 v40, v40, v41, 4 bitop3:0x36
	v_mad_u64_u32 v[148:149], s[12:13], v142, s12, v[0:1]
	s_addc_u32 s9, s9, s19
	v_bitop3_b32 v42, v42, v41, 3 bitop3:0x6c
	v_lshlrev_b32_e32 v161, 4, v40
	s_lshl_b32 s12, s40, 1
	v_or_b32_e32 v38, v38, v0
	v_mov_b64_e32 v[40:41], s[8:9]
	v_lshl_add_u64 v[150:151], s[2:3], 0, v[0:1]
	v_lshl_add_u64 v[38:39], s[2:3], 0, v[38:39]
	v_mad_i64_i32 v[40:41], s[2:3], s12, v142, v[40:41]
	v_mov_b32_e32 v2, v1
	v_mov_b32_e32 v3, v1
	v_add_u32_e32 v37, 0, v162
	v_add_u32_e32 v60, 0, v148
	s_mov_b64 s[2:3], 0x6000
	v_mov_b32_e32 v157, v156
	v_mov_b32_e32 v36, 0
	v_lshlrev_b32_e32 v143, 7, v43
	v_mul_u32_u24_e32 v147, 0x90, v43
	v_lshlrev_b32_e32 v160, 4, v42
	v_lshl_add_u64 v[152:153], v[38:39], 0, s[2:3]
	s_waitcnt vmcnt(0)
	s_barrier
	v_lshl_add_u64 v[38:39], v[40:41], 0, v[0:1]
	v_mov_b32_e32 v0, v1
	v_mov_b64_e32 v[42:43], v[2:3]
	v_mov_b64_e32 v[54:55], v[2:3]
	v_mov_b64_e32 v[46:47], v[2:3]
	v_mov_b64_e32 v[58:59], v[2:3]
	v_mov_b64_e32 v[50:51], v[2:3]
	v_mov_b64_e32 v[70:71], v[2:3]
	v_mov_b64_e32 v[74:75], v[2:3]
	s_mov_b32 s6, 3
	s_mov_b32 s11, 0
	s_movk_i32 s7, 0x80
	v_lshl_add_u64 v[154:155], s[0:1], 0, v[38:39]
	v_mov_b64_e32 v[40:41], v[0:1]
	v_mov_b64_e32 v[52:53], v[0:1]
	v_mov_b64_e32 v[44:45], v[0:1]
	ds_write_b128 v37, v[4:7]
	ds_write_b128 v60, v[32:35] offset:8192
	ds_write_b128 v37, v[8:11] offset:17408
	ds_write_b128 v60, v[20:23] offset:25600
	v_mov_b64_e32 v[62:63], v[2:3]
	v_mov_b64_e32 v[56:57], v[0:1]
	v_mov_b64_e32 v[48:49], v[0:1]
	v_mov_b64_e32 v[68:69], v[0:1]
	v_mov_b64_e32 v[60:61], v[0:1]
	v_mov_b64_e32 v[72:73], v[0:1]
	v_mov_b64_e32 v[2:3], v[156:157]
	v_mov_b32_e32 v37, v36
	v_mov_b32_e32 v38, v36
	v_mov_b32_e32 v39, v36
	v_mov_b32_e32 v64, v36
	v_mov_b32_e32 v65, v36
	v_mov_b32_e32 v66, v36
	v_mov_b32_e32 v67, v36
	s_waitcnt lgkmcnt(0)
	s_barrier
	.p2align	6

.LBB0_1301:
	v_and_b32_e32 v19, 15, v18
	s_waitcnt vmcnt(0)
	v_and_b32_e32 v20, 48, v18
	v_lshlrev_b32_e32 v18, 2, v18
	v_lshlrev_b32_e32 v19, 6, v19
	v_and_b32_e32 v18, 32, v18
	s_lshl_b32 s12, s12, 12
	v_or_b32_e32 v21, v19, v20
	s_lshl_b32 s13, s13, 13
	v_bitop3_b32 v19, v19, v18, v20 bitop3:0x36
	s_and_b32 s12, s12, 0x3000
	v_lshl_add_u64 v[8:9], v[8:9], 0, s[24:25]
	s_add_i32 m0, s4, 0x18000
	s_and_b32 s17, s62, 0x700
	v_bitop3_b32 v18, v21, s13, v18 bitop3:0xde
	v_or_b32_e32 v141, s12, v19
	s_waitcnt vmcnt(2)
	s_barrier
	global_load_lds_dwordx4 v[8:9], off
	v_lshl_add_u64 v[6:7], v[6:7], 0, s[24:25]
	s_add_i32 m0, s4, 0x1a000
	s_add_i32 s12, s4, 0x8000
	s_add_i32 s13, s4, 0xa000
	global_load_lds_dwordx4 v[6:7], off
	v_lshl_add_u64 v[4:5], v[4:5], 0, s[24:25]
	s_mov_b32 m0, s12
	s_add_u32 s40, s8, 0x10080
	global_load_lds_dwordx4 v[4:5], off
	v_lshl_add_u64 v[2:3], v[2:3], 0, s[24:25]
	s_mov_b32 m0, s13
	s_addc_u32 s41, s9, 0
	global_load_lds_dwordx4 v[2:3], off
	v_lshl_add_u64 v[2:3], s[40:41], 0, v[0:1]
	s_add_i32 m0, s4, 0x1c000
	s_add_i32 s16, s16, s17
	global_load_lds_dwordx4 v[2:3], off
	v_lshl_add_u64 v[2:3], s[40:41], 0, v[134:135]
	s_add_i32 m0, s4, 0x1e000
	s_ashr_i32 s17, s16, 31
	global_load_lds_dwordx4 v[2:3], off
	v_lshlrev_b32_e32 v2, 13, v14
	v_and_b32_e32 v2, 0x7fffc000, v2
	s_lshl_b64 s[16:17], s[16:17], 11
	v_lshl_add_u32 v2, v15, 10, v2
	v_or_b32_e32 v2, v2, v16
	s_add_u32 s16, s72, s16
	v_add_lshl_u32 v2, v2, v17, 1
	v_mov_b32_e32 v3, v1
	s_addc_u32 s17, s73, s17
	v_lshl_add_u64 v[136:137], s[16:17], 0, v[2:3]
	v_lshlrev_b32_e32 v2, 13, v10
	v_and_b32_e32 v2, 0x7fffc000, v2
	v_lshl_add_u32 v2, v11, 10, v2
	v_or_b32_e32 v2, v2, v12
	s_waitcnt vmcnt(6)
	v_add_lshl_u32 v2, v2, v13, 1
	v_lshl_add_u64 v[138:139], s[16:17], 0, v[2:3]
	v_mov_b32_e32 v2, 0
	s_mov_b32 s16, -2
	s_mov_b64 s[40:41], 0x3188080
	v_add_u32_e32 v142, 0, v18
	v_mov_b32_e32 v3, v2
	v_mov_b32_e32 v4, v2
	v_mov_b32_e32 v5, v2
	v_mov_b32_e32 v6, v2
	v_mov_b32_e32 v7, v2
	v_mov_b32_e32 v8, v2
	v_mov_b32_e32 v9, v2
	v_mov_b32_e32 v18, v2
	v_mov_b32_e32 v19, v2
	v_mov_b32_e32 v20, v2
	v_mov_b32_e32 v21, v2
	v_mov_b32_e32 v22, v2
	v_mov_b32_e32 v23, v2
	v_mov_b32_e32 v24, v2
	v_mov_b32_e32 v25, v2
	v_mov_b32_e32 v34, v2
	v_mov_b32_e32 v35, v2
	v_mov_b32_e32 v36, v2
	v_mov_b32_e32 v37, v2
	v_mov_b32_e32 v38, v2
	v_mov_b32_e32 v39, v2
	v_mov_b32_e32 v40, v2
	v_mov_b32_e32 v41, v2
	v_mov_b32_e32 v50, v2
	v_mov_b32_e32 v51, v2
	v_mov_b32_e32 v52, v2
	v_mov_b32_e32 v53, v2
	v_mov_b32_e32 v54, v2
	v_mov_b32_e32 v55, v2
	v_mov_b32_e32 v56, v2
	v_mov_b32_e32 v57, v2
	v_mov_b32_e32 v10, v2
	v_mov_b32_e32 v11, v2
	v_mov_b32_e32 v12, v2
	v_mov_b32_e32 v13, v2
	v_mov_b32_e32 v14, v2
	v_mov_b32_e32 v15, v2
	v_mov_b32_e32 v16, v2
	v_mov_b32_e32 v17, v2
	v_mov_b32_e32 v26, v2
	v_mov_b32_e32 v27, v2
	v_mov_b32_e32 v28, v2
	v_mov_b32_e32 v29, v2
	v_mov_b32_e32 v30, v2
	v_mov_b32_e32 v31, v2
	v_mov_b32_e32 v32, v2
	v_mov_b32_e32 v33, v2
	v_mov_b32_e32 v42, v2
	v_mov_b32_e32 v43, v2
	v_mov_b32_e32 v44, v2
	v_mov_b32_e32 v45, v2
	v_mov_b32_e32 v46, v2
	v_mov_b32_e32 v47, v2
	v_mov_b32_e32 v48, v2
	v_mov_b32_e32 v49, v2
	v_mov_b32_e32 v58, v2
	v_mov_b32_e32 v59, v2
	v_mov_b32_e32 v60, v2
	v_mov_b32_e32 v61, v2
	v_mov_b32_e32 v62, v2
	v_mov_b32_e32 v63, v2
	v_mov_b32_e32 v64, v2
	v_mov_b32_e32 v65, v2
	v_mov_b32_e32 v66, v2
	v_mov_b32_e32 v67, v2
	v_mov_b32_e32 v68, v2
	v_mov_b32_e32 v69, v2
	v_mov_b32_e32 v70, v2
	v_mov_b32_e32 v71, v2
	v_mov_b32_e32 v72, v2
	v_mov_b32_e32 v73, v2
	v_mov_b32_e32 v82, v2
	v_mov_b32_e32 v83, v2
	v_mov_b32_e32 v84, v2
	v_mov_b32_e32 v85, v2
	v_mov_b32_e32 v86, v2
	v_mov_b32_e32 v87, v2
	v_mov_b32_e32 v88, v2
	v_mov_b32_e32 v89, v2
	v_mov_b32_e32 v98, v2
	v_mov_b32_e32 v99, v2
	v_mov_b32_e32 v100, v2
	v_mov_b32_e32 v101, v2
	v_mov_b32_e32 v102, v2
	v_mov_b32_e32 v103, v2
	v_mov_b32_e32 v104, v2
	v_mov_b32_e32 v105, v2
	v_mov_b32_e32 v114, v2
	v_mov_b32_e32 v115, v2
	v_mov_b32_e32 v116, v2
	v_mov_b32_e32 v117, v2
	v_mov_b32_e32 v118, v2
	v_mov_b32_e32 v119, v2
	v_mov_b32_e32 v120, v2
	v_mov_b32_e32 v121, v2
	v_mov_b32_e32 v74, v2
	v_mov_b32_e32 v75, v2
	v_mov_b32_e32 v76, v2
	v_mov_b32_e32 v77, v2
	v_mov_b32_e32 v78, v2
	v_mov_b32_e32 v79, v2
	v_mov_b32_e32 v80, v2
	v_mov_b32_e32 v81, v2
	v_mov_b32_e32 v90, v2
	v_mov_b32_e32 v91, v2
	v_mov_b32_e32 v92, v2
	v_mov_b32_e32 v93, v2
	v_mov_b32_e32 v94, v2
	v_mov_b32_e32 v95, v2
	v_mov_b32_e32 v96, v2
	v_mov_b32_e32 v97, v2
	v_mov_b32_e32 v106, v2
	v_mov_b32_e32 v107, v2
	v_mov_b32_e32 v108, v2
	v_mov_b32_e32 v109, v2
	v_mov_b32_e32 v110, v2
	v_mov_b32_e32 v111, v2
	v_mov_b32_e32 v112, v2
	v_mov_b32_e32 v113, v2
	v_mov_b32_e32 v122, v2
	v_mov_b32_e32 v123, v2
	v_mov_b32_e32 v124, v2
	v_mov_b32_e32 v125, v2
	v_mov_b32_e32 v126, v2
	v_mov_b32_e32 v127, v2
	v_mov_b32_e32 v128, v2
	v_mov_b32_e32 v129, v2
	s_barrier
	.p2align	6
